# attention tile loop: removed 4 dead scalar copies and the dead 64-bit offset update per 2 tiles; scan prefetch gate falls through
# speedup vs baseline: 1.0013x; 1.0013x over previous
; __device__ __forceinline__ void attn_unit(const Params& p, int b, int h, int q0, int nkeys, char* smem) {
;     ...
;     for (int kt2 = 0; kt2 < nt; kt2 += 2) {
;         ATT_BODY(kt2, b, a)
;         ATT_BODY(kt2 + 1, a, b)
;     }
.LBB0_459:
	v_add_u32_e32 v178, 0x6000, v178
	v_add_u32_e32 v179, 0x6000, v179
	v_add_u32_e32 v191, 0x6000, v191
	v_add_u32_e32 v208, 0x100, v208
	v_add_u32_e32 v120, 0x100, v120
	s_add_i32 s42, s42, 2
	s_cmp_lt_u32 s43, s35
	s_waitcnt lgkmcnt(0)
	s_barrier
	s_cbranch_scc0 .LBB0_447
.LBB0_460:
	s_add_i32 s43, s42, -1
	s_cmp_lt_u32 s43, s35
	s_cselect_b64 s[0:1], -1, 0
	s_cmp_ge_u32 s43, s35
	s_cbranch_scc1 .LBB0_462
	global_load_dwordx4 v[44:47], v178, s[98:99] offset:-4096
	global_load_dwordx4 v[48:51], v178, s[98:99]
	global_load_dwordx4 v[52:55], v179, s[98:99] offset:-4096
	global_load_dwordx4 v[56:59], v120, s[100:101] offset:256
	global_load_dwordx4 v[60:63], v208, s[100:101] offset:256
